# GEMM tile headers zero the 128 accumulators with 64 v_mov_b64 instead of 128 v_mov_b32
# baseline (speedup 1.0000x reference)
; template <class Epi, class Sched, bool ALIGN_EPI = false, bool SP2 = false>
; __device__ __forceinline__ void gemm_phase(PG8_LAS unsigned char* lds, const Gemm g, const Sched& S, const Epi& E) {
;     ...
;         const bool has_next = S.next(ui + 1, nxt);
;         const char* nA = has_next ? (const char*)g.A + (size_t)nxt.pm * tstep : cA; const char* nB = has_next ? (const char*)g.Bt + (size_t)nxt.pn * tstep : cB;
;         for (int t = 0; t < nt; t += 2) {
;             const bool last = (t == nt - 2);
;             const char* a1 = cA + (size_t)(t + 1) * kstep;
;             const char* a2 = last ? nA : cA + (size_t)(t + 2) * kstep; const char* b2 = last ? nB : cB + (size_t)(t + 2) * kstep;
;             const char* a3 = a2 + kstep; const char* b3 = b2 + kstep;
;     ...
; #pragma unroll
;         for (int a = 0; a < 2; ++a)
; #pragma unroll
;             for (int b = 0; b < 2; ++b)
; #pragma unroll
;                 for (int m = 0; m < 4; ++m)
; #pragma unroll
;                     for (int n = 0; n < 2; ++n) acc[a][b][m][n] = (f32x4){0.f, 0.f, 0.f, 0.f};
.LBB0_426:
	s_ashr_i32 s23, s22, 31
	s_lshl_b64 s[24:25], s[22:23], 19
	s_add_u32 s24, s92, s24
	s_addc_u32 s25, s93, s25
	s_and_b64 s[26:27], s[2:3], exec
	s_cselect_b32 s5, s25, s9
	s_cselect_b32 s7, s24, s8
	s_ashr_i32 s21, s20, 31
	s_lshl_b64 s[26:27], s[20:21], 19
	s_add_u32 s26, s10, s26
	s_addc_u32 s27, s11, s27
	s_and_b64 s[36:37], s[2:3], exec
	s_cselect_b32 s12, s27, s29
	s_cselect_b32 s21, s26, s28
	s_add_u32 s8, s8, 0x40080
	s_addc_u32 s9, s9, 0
	s_add_u32 s23, s28, 0x100
	v_mov_b64_e32 v[0:1], 0
	v_mov_b64_e32 v[2:3], 0
	v_mov_b64_e32 v[4:5], 0
	v_mov_b64_e32 v[6:7], 0
	v_mov_b64_e32 v[8:9], 0
	v_mov_b64_e32 v[10:11], 0
	v_mov_b64_e32 v[12:13], 0
	v_mov_b64_e32 v[14:15], 0
	v_mov_b64_e32 v[16:17], 0
	v_mov_b64_e32 v[18:19], 0
	v_mov_b64_e32 v[20:21], 0
	v_mov_b64_e32 v[22:23], 0
	v_mov_b64_e32 v[24:25], 0
	v_mov_b64_e32 v[26:27], 0
	v_mov_b64_e32 v[28:29], 0
	v_mov_b64_e32 v[30:31], 0
	v_mov_b64_e32 v[32:33], 0
	v_mov_b64_e32 v[34:35], 0
	v_mov_b64_e32 v[36:37], 0
	v_mov_b64_e32 v[38:39], 0
	v_mov_b64_e32 v[40:41], 0
	v_mov_b64_e32 v[42:43], 0
	v_mov_b64_e32 v[44:45], 0
	v_mov_b64_e32 v[46:47], 0
	v_mov_b64_e32 v[48:49], 0
	v_mov_b64_e32 v[50:51], 0
	v_mov_b64_e32 v[52:53], 0
	v_mov_b64_e32 v[54:55], 0
	v_mov_b64_e32 v[56:57], 0
	v_mov_b64_e32 v[58:59], 0
	v_mov_b64_e32 v[60:61], 0
	v_mov_b64_e32 v[62:63], 0
	v_mov_b64_e32 v[64:65], 0
	v_mov_b64_e32 v[66:67], 0
	v_mov_b64_e32 v[68:69], 0
	v_mov_b64_e32 v[70:71], 0
	v_mov_b64_e32 v[72:73], 0
	v_mov_b64_e32 v[74:75], 0
	v_mov_b64_e32 v[76:77], 0
	v_mov_b64_e32 v[78:79], 0
	v_mov_b64_e32 v[80:81], 0
	v_mov_b64_e32 v[82:83], 0
	v_mov_b64_e32 v[84:85], 0
	v_mov_b64_e32 v[86:87], 0
	v_mov_b64_e32 v[88:89], 0
	v_mov_b64_e32 v[90:91], 0
	v_mov_b64_e32 v[92:93], 0
	v_mov_b64_e32 v[94:95], 0
	v_mov_b64_e32 v[96:97], 0
	v_mov_b64_e32 v[98:99], 0
	v_mov_b64_e32 v[100:101], 0
	v_mov_b64_e32 v[102:103], 0
	v_mov_b64_e32 v[104:105], 0
	v_mov_b64_e32 v[106:107], 0
	v_mov_b64_e32 v[108:109], 0
	v_mov_b64_e32 v[110:111], 0
	v_mov_b64_e32 v[112:113], 0
	v_mov_b64_e32 v[114:115], 0
	v_mov_b64_e32 v[116:117], 0
	v_mov_b64_e32 v[118:119], 0
	v_mov_b64_e32 v[120:121], 0
	v_mov_b64_e32 v[122:123], 0
	v_mov_b64_e32 v[124:125], 0
	v_mov_b64_e32 v[126:127], 0
	s_addc_u32 s38, s29, 0
	s_mov_b32 s39, -2

; template <class Epi, class Sched, bool ALIGN_EPI = false, bool SP2 = false>
; __device__ __forceinline__ void gemm_phase(PG8_LAS unsigned char* lds, const Gemm g, const Sched& S, const Epi& E) {
;     ...
;         const bool has_next = S.next(ui + 1, nxt);
;         const char* nA = has_next ? (const char*)g.A + (size_t)nxt.pm * tstep : cA; const char* nB = has_next ? (const char*)g.Bt + (size_t)nxt.pn * tstep : cB;
;         for (int t = 0; t < nt; t += 2) {
;             const bool last = (t == nt - 2);
;             const char* a1 = cA + (size_t)(t + 1) * kstep;
;             const char* a2 = last ? nA : cA + (size_t)(t + 2) * kstep; const char* b2 = last ? nB : cB + (size_t)(t + 2) * kstep;
;             const char* a3 = a2 + kstep; const char* b3 = b2 + kstep;
;     ...
; #pragma unroll
;         for (int a = 0; a < 2; ++a)
; #pragma unroll
;             for (int b = 0; b < 2; ++b)
; #pragma unroll
;                 for (int m = 0; m < 4; ++m)
; #pragma unroll
;                     for (int n = 0; n < 2; ++n) acc[a][b][m][n] = (f32x4){0.f, 0.f, 0.f, 0.f};
.LBB0_1246:
	s_ashr_i32 s29, s28, 31
	s_lshl_b64 s[8:9], s[28:29], 19
	s_add_u32 s30, s92, s8
	s_addc_u32 s31, s93, s9
	s_and_b64 s[8:9], s[2:3], exec
	s_cselect_b32 s10, s31, s5
	s_cselect_b32 s11, s30, s4
	s_ashr_i32 s27, s26, 31
	s_lshl_b64 s[8:9], s[26:27], 19
	s_add_u32 s34, s37, s8
	s_addc_u32 s35, s38, s9
	s_and_b64 s[8:9], s[2:3], exec
	s_cselect_b32 s27, s35, s7
	s_cselect_b32 s29, s34, s6
	s_add_u32 s4, s4, 0x40080
	s_addc_u32 s5, s5, 0
	s_add_u32 s52, s6, 0x100
	v_mov_b64_e32 v[0:1], 0
	v_mov_b64_e32 v[2:3], 0
	v_mov_b64_e32 v[4:5], 0
	v_mov_b64_e32 v[6:7], 0
	v_mov_b64_e32 v[8:9], 0
	v_mov_b64_e32 v[10:11], 0
	v_mov_b64_e32 v[12:13], 0
	v_mov_b64_e32 v[14:15], 0
	v_mov_b64_e32 v[16:17], 0
	v_mov_b64_e32 v[18:19], 0
	v_mov_b64_e32 v[20:21], 0
	v_mov_b64_e32 v[22:23], 0
	v_mov_b64_e32 v[24:25], 0
	v_mov_b64_e32 v[26:27], 0
	v_mov_b64_e32 v[28:29], 0
	v_mov_b64_e32 v[30:31], 0
	v_mov_b64_e32 v[32:33], 0
	v_mov_b64_e32 v[34:35], 0
	v_mov_b64_e32 v[36:37], 0
	v_mov_b64_e32 v[38:39], 0
	v_mov_b64_e32 v[40:41], 0
	v_mov_b64_e32 v[42:43], 0
	v_mov_b64_e32 v[44:45], 0
	v_mov_b64_e32 v[46:47], 0
	v_mov_b64_e32 v[48:49], 0
	v_mov_b64_e32 v[50:51], 0
	v_mov_b64_e32 v[52:53], 0
	v_mov_b64_e32 v[54:55], 0
	v_mov_b64_e32 v[56:57], 0
	v_mov_b64_e32 v[58:59], 0
	v_mov_b64_e32 v[60:61], 0
	v_mov_b64_e32 v[62:63], 0
	v_mov_b64_e32 v[64:65], 0
	v_mov_b64_e32 v[66:67], 0
	v_mov_b64_e32 v[68:69], 0
	v_mov_b64_e32 v[70:71], 0
	v_mov_b64_e32 v[72:73], 0
	v_mov_b64_e32 v[74:75], 0
	v_mov_b64_e32 v[76:77], 0
	v_mov_b64_e32 v[78:79], 0
	v_mov_b64_e32 v[80:81], 0
	v_mov_b64_e32 v[82:83], 0
	v_mov_b64_e32 v[84:85], 0
	v_mov_b64_e32 v[86:87], 0
	v_mov_b64_e32 v[88:89], 0
	v_mov_b64_e32 v[90:91], 0
	v_mov_b64_e32 v[92:93], 0
	v_mov_b64_e32 v[94:95], 0
	v_mov_b64_e32 v[96:97], 0
	v_mov_b64_e32 v[98:99], 0
	v_mov_b64_e32 v[100:101], 0
	v_mov_b64_e32 v[102:103], 0
	v_mov_b64_e32 v[104:105], 0
	v_mov_b64_e32 v[106:107], 0
	v_mov_b64_e32 v[108:109], 0
	v_mov_b64_e32 v[110:111], 0
	v_mov_b64_e32 v[112:113], 0
	v_mov_b64_e32 v[114:115], 0
	v_mov_b64_e32 v[116:117], 0
	v_mov_b64_e32 v[118:119], 0
	v_mov_b64_e32 v[120:121], 0
	v_mov_b64_e32 v[122:123], 0
	v_mov_b64_e32 v[124:125], 0
	v_mov_b64_e32 v[126:127], 0
	s_addc_u32 s53, s7, 0
	s_mov_b32 s56, -2
	s_waitcnt vmcnt(0)

; template <class Epi, class Sched, bool ALIGN_EPI = false, bool SP2 = false>
; __device__ __forceinline__ void gemm_phase(PG8_LAS unsigned char* lds, const Gemm g, const Sched& S, const Epi& E) {
;     ...
;         const bool has_next = S.next(ui + 1, nxt);
;         const char* nA = has_next ? (const char*)g.A + (size_t)nxt.pm * tstep : cA; const char* nB = has_next ? (const char*)g.Bt + (size_t)nxt.pn * tstep : cB;
;         for (int t = 0; t < nt; t += 2) {
;             const bool last = (t == nt - 2);
;             const char* a1 = cA + (size_t)(t + 1) * kstep;
;             const char* a2 = last ? nA : cA + (size_t)(t + 2) * kstep; const char* b2 = last ? nB : cB + (size_t)(t + 2) * kstep;
;             const char* a3 = a2 + kstep; const char* b3 = b2 + kstep;
;     ...
; #pragma unroll
;         for (int a = 0; a < 2; ++a)
; #pragma unroll
;             for (int b = 0; b < 2; ++b)
; #pragma unroll
;                 for (int m = 0; m < 4; ++m)
; #pragma unroll
;                     for (int n = 0; n < 2; ++n) acc[a][b][m][n] = (f32x4){0.f, 0.f, 0.f, 0.f};
.LBB0_1270:
	s_ashr_i32 s21, s20, 31
	s_lshl_b64 s[22:23], s[20:21], 18
	s_add_u32 s22, s48, s22
	s_addc_u32 s23, s49, s23
	s_and_b64 s[24:25], s[4:5], exec
	s_cselect_b32 s21, s23, s29
	s_cselect_b32 s56, s22, s28
	s_ashr_i32 s19, s18, 31
	s_lshl_b64 s[24:25], s[18:19], 18
	s_add_u32 s24, s78, s24
	s_addc_u32 s25, s79, s25
	s_and_b64 s[34:35], s[4:5], exec
	s_cselect_b32 s19, s25, s31
	s_cselect_b32 s57, s24, s30
	s_add_u32 s28, s28, 0x20080
	s_addc_u32 s29, s29, 0
	s_add_u32 s61, s30, 0x100
	v_mov_b64_e32 v[0:1], 0
	v_mov_b64_e32 v[2:3], 0
	v_mov_b64_e32 v[4:5], 0
	v_mov_b64_e32 v[6:7], 0
	v_mov_b64_e32 v[8:9], 0
	v_mov_b64_e32 v[10:11], 0
	v_mov_b64_e32 v[12:13], 0
	v_mov_b64_e32 v[14:15], 0
	v_mov_b64_e32 v[16:17], 0
	v_mov_b64_e32 v[18:19], 0
	v_mov_b64_e32 v[20:21], 0
	v_mov_b64_e32 v[22:23], 0
	v_mov_b64_e32 v[24:25], 0
	v_mov_b64_e32 v[26:27], 0
	v_mov_b64_e32 v[28:29], 0
	v_mov_b64_e32 v[30:31], 0
	v_mov_b64_e32 v[32:33], 0
	v_mov_b64_e32 v[34:35], 0
	v_mov_b64_e32 v[36:37], 0
	v_mov_b64_e32 v[38:39], 0
	v_mov_b64_e32 v[40:41], 0
	v_mov_b64_e32 v[42:43], 0
	v_mov_b64_e32 v[44:45], 0
	v_mov_b64_e32 v[46:47], 0
	v_mov_b64_e32 v[48:49], 0
	v_mov_b64_e32 v[50:51], 0
	v_mov_b64_e32 v[52:53], 0
	v_mov_b64_e32 v[54:55], 0
	v_mov_b64_e32 v[56:57], 0
	v_mov_b64_e32 v[58:59], 0
	v_mov_b64_e32 v[60:61], 0
	v_mov_b64_e32 v[62:63], 0
	v_mov_b64_e32 v[64:65], 0
	v_mov_b64_e32 v[66:67], 0
	v_mov_b64_e32 v[68:69], 0
	v_mov_b64_e32 v[70:71], 0
	v_mov_b64_e32 v[72:73], 0
	v_mov_b64_e32 v[74:75], 0
	v_mov_b64_e32 v[76:77], 0
	v_mov_b64_e32 v[78:79], 0
	v_mov_b64_e32 v[80:81], 0
	v_mov_b64_e32 v[82:83], 0
	v_mov_b64_e32 v[84:85], 0
	v_mov_b64_e32 v[86:87], 0
	v_mov_b64_e32 v[88:89], 0
	v_mov_b64_e32 v[90:91], 0
	v_mov_b64_e32 v[92:93], 0
	v_mov_b64_e32 v[94:95], 0
	v_mov_b64_e32 v[96:97], 0
	v_mov_b64_e32 v[98:99], 0
	v_mov_b64_e32 v[100:101], 0
	v_mov_b64_e32 v[102:103], 0
	v_mov_b64_e32 v[104:105], 0
	v_mov_b64_e32 v[106:107], 0
	v_mov_b64_e32 v[108:109], 0
	v_mov_b64_e32 v[110:111], 0
	v_mov_b64_e32 v[112:113], 0
	v_mov_b64_e32 v[114:115], 0
	v_mov_b64_e32 v[116:117], 0
	v_mov_b64_e32 v[118:119], 0
	v_mov_b64_e32 v[120:121], 0
	v_mov_b64_e32 v[122:123], 0
	v_mov_b64_e32 v[124:125], 0
	v_mov_b64_e32 v[126:127], 0
	s_addc_u32 s62, s31, 0
	s_mov_b32 s63, -2
	s_waitcnt vmcnt(0)

; template <class Epi, class Sched, bool ALIGN_EPI = false, bool SP2 = false>
; __device__ __forceinline__ void gemm_phase(PG8_LAS unsigned char* lds, const Gemm g, const Sched& S, const Epi& E) {
;     ...
;         const bool has_next = S.next(ui + 1, nxt);
;         const char* nA = has_next ? (const char*)g.A + (size_t)nxt.pm * tstep : cA; const char* nB = has_next ? (const char*)g.Bt + (size_t)nxt.pn * tstep : cB;
;         for (int t = 0; t < nt; t += 2) {
;             const bool last = (t == nt - 2);
;             const char* a1 = cA + (size_t)(t + 1) * kstep;
;             const char* a2 = last ? nA : cA + (size_t)(t + 2) * kstep; const char* b2 = last ? nB : cB + (size_t)(t + 2) * kstep;
;             const char* a3 = a2 + kstep; const char* b3 = b2 + kstep;
;     ...
; #pragma unroll
;         for (int a = 0; a < 2; ++a)
; #pragma unroll
;             for (int b = 0; b < 2; ++b)
; #pragma unroll
;                 for (int m = 0; m < 4; ++m)
; #pragma unroll
;                     for (int n = 0; n < 2; ++n) acc[a][b][m][n] = (f32x4){0.f, 0.f, 0.f, 0.f};
.LBB0_1294:
	s_ashr_i32 s29, s28, 31
	s_lshl_b64 s[10:11], s[28:29], 19
	s_add_u32 s30, s92, s10
	s_addc_u32 s31, s93, s11
	s_and_b64 s[10:11], s[4:5], exec
	s_cselect_b32 s12, s31, s7
	s_cselect_b32 s13, s30, s6
	s_ashr_i32 s27, s26, 31
	s_lshl_b64 s[10:11], s[26:27], 19
	s_add_u32 s34, s37, s10
	s_addc_u32 s35, s38, s11
	s_and_b64 s[10:11], s[4:5], exec
	s_cselect_b32 s27, s35, s9
	s_cselect_b32 s29, s34, s8
	s_add_u32 s6, s6, 0x40080
	s_addc_u32 s7, s7, 0
	s_add_u32 s52, s8, 0x100
	v_mov_b64_e32 v[0:1], 0
	v_mov_b64_e32 v[2:3], 0
	v_mov_b64_e32 v[4:5], 0
	v_mov_b64_e32 v[6:7], 0
	v_mov_b64_e32 v[8:9], 0
	v_mov_b64_e32 v[10:11], 0
	v_mov_b64_e32 v[12:13], 0
	v_mov_b64_e32 v[14:15], 0
	v_mov_b64_e32 v[16:17], 0
	v_mov_b64_e32 v[18:19], 0
	v_mov_b64_e32 v[20:21], 0
	v_mov_b64_e32 v[22:23], 0
	v_mov_b64_e32 v[24:25], 0
	v_mov_b64_e32 v[26:27], 0
	v_mov_b64_e32 v[28:29], 0
	v_mov_b64_e32 v[30:31], 0
	v_mov_b64_e32 v[32:33], 0
	v_mov_b64_e32 v[34:35], 0
	v_mov_b64_e32 v[36:37], 0
	v_mov_b64_e32 v[38:39], 0
	v_mov_b64_e32 v[40:41], 0
	v_mov_b64_e32 v[42:43], 0
	v_mov_b64_e32 v[44:45], 0
	v_mov_b64_e32 v[46:47], 0
	v_mov_b64_e32 v[48:49], 0
	v_mov_b64_e32 v[50:51], 0
	v_mov_b64_e32 v[52:53], 0
	v_mov_b64_e32 v[54:55], 0
	v_mov_b64_e32 v[56:57], 0
	v_mov_b64_e32 v[58:59], 0
	v_mov_b64_e32 v[60:61], 0
	v_mov_b64_e32 v[62:63], 0
	v_mov_b64_e32 v[64:65], 0
	v_mov_b64_e32 v[66:67], 0
	v_mov_b64_e32 v[68:69], 0
	v_mov_b64_e32 v[70:71], 0
	v_mov_b64_e32 v[72:73], 0
	v_mov_b64_e32 v[74:75], 0
	v_mov_b64_e32 v[76:77], 0
	v_mov_b64_e32 v[78:79], 0
	v_mov_b64_e32 v[80:81], 0
	v_mov_b64_e32 v[82:83], 0
	v_mov_b64_e32 v[84:85], 0
	v_mov_b64_e32 v[86:87], 0
	v_mov_b64_e32 v[88:89], 0
	v_mov_b64_e32 v[90:91], 0
	v_mov_b64_e32 v[92:93], 0
	v_mov_b64_e32 v[94:95], 0
	v_mov_b64_e32 v[96:97], 0
	v_mov_b64_e32 v[98:99], 0
	v_mov_b64_e32 v[100:101], 0
	v_mov_b64_e32 v[102:103], 0
	v_mov_b64_e32 v[104:105], 0
	v_mov_b64_e32 v[106:107], 0
	v_mov_b64_e32 v[108:109], 0
	v_mov_b64_e32 v[110:111], 0
	v_mov_b64_e32 v[112:113], 0
	v_mov_b64_e32 v[114:115], 0
	v_mov_b64_e32 v[116:117], 0
	v_mov_b64_e32 v[118:119], 0
	v_mov_b64_e32 v[120:121], 0
	v_mov_b64_e32 v[122:123], 0
	v_mov_b64_e32 v[124:125], 0
	v_mov_b64_e32 v[126:127], 0
	s_addc_u32 s53, s9, 0
	s_mov_b32 s68, -2
	s_waitcnt vmcnt(0)

; template <class Epi, class Sched, bool ALIGN_EPI = false, bool SP2 = false>
; __device__ __forceinline__ void gemm_phase(PG8_LAS unsigned char* lds, const Gemm g, const Sched& S, const Epi& E) {
;     ...
;         const bool has_next = S.next(ui + 1, nxt);
;         const char* nA = has_next ? (const char*)g.A + (size_t)nxt.pm * tstep : cA; const char* nB = has_next ? (const char*)g.Bt + (size_t)nxt.pn * tstep : cB;
;         for (int t = 0; t < nt; t += 2) {
;             const bool last = (t == nt - 2);
;             const char* a1 = cA + (size_t)(t + 1) * kstep;
;             const char* a2 = last ? nA : cA + (size_t)(t + 2) * kstep; const char* b2 = last ? nB : cB + (size_t)(t + 2) * kstep;
;             const char* a3 = a2 + kstep; const char* b3 = b2 + kstep;
;     ...
; #pragma unroll
;         for (int a = 0; a < 2; ++a)
; #pragma unroll
;             for (int b = 0; b < 2; ++b)
; #pragma unroll
;                 for (int m = 0; m < 4; ++m)
; #pragma unroll
;                     for (int n = 0; n < 2; ++n) acc[a][b][m][n] = (f32x4){0.f, 0.f, 0.f, 0.f};
.LBB0_1318:
	s_ashr_i32 s23, s22, 31
	s_lshl_b64 s[24:25], s[22:23], 18
	s_add_u32 s24, s58, s24
	s_addc_u32 s25, s59, s25
	s_and_b64 s[26:27], s[2:3], exec
	s_cselect_b32 s23, s25, s31
	s_cselect_b32 s53, s24, s30
	s_ashr_i32 s21, s20, 31
	s_lshl_b64 s[26:27], s[20:21], 18
	s_add_u32 s26, s76, s26
	s_addc_u32 s27, s77, s27
	s_and_b64 s[36:37], s[2:3], exec
	s_cselect_b32 s21, s27, s35
	s_cselect_b32 s62, s26, s34
	s_add_u32 s30, s30, 0x20080
	s_addc_u32 s31, s31, 0
	s_add_u32 s63, s34, 0x100
	v_mov_b64_e32 v[0:1], 0
	v_mov_b64_e32 v[2:3], 0
	v_mov_b64_e32 v[4:5], 0
	v_mov_b64_e32 v[6:7], 0
	v_mov_b64_e32 v[8:9], 0
	v_mov_b64_e32 v[10:11], 0
	v_mov_b64_e32 v[12:13], 0
	v_mov_b64_e32 v[14:15], 0
	v_mov_b64_e32 v[16:17], 0
	v_mov_b64_e32 v[18:19], 0
	v_mov_b64_e32 v[20:21], 0
	v_mov_b64_e32 v[22:23], 0
	v_mov_b64_e32 v[24:25], 0
	v_mov_b64_e32 v[26:27], 0
	v_mov_b64_e32 v[28:29], 0
	v_mov_b64_e32 v[30:31], 0
	v_mov_b64_e32 v[32:33], 0
	v_mov_b64_e32 v[34:35], 0
	v_mov_b64_e32 v[36:37], 0
	v_mov_b64_e32 v[38:39], 0
	v_mov_b64_e32 v[40:41], 0
	v_mov_b64_e32 v[42:43], 0
	v_mov_b64_e32 v[44:45], 0
	v_mov_b64_e32 v[46:47], 0
	v_mov_b64_e32 v[48:49], 0
	v_mov_b64_e32 v[50:51], 0
	v_mov_b64_e32 v[52:53], 0
	v_mov_b64_e32 v[54:55], 0
	v_mov_b64_e32 v[56:57], 0
	v_mov_b64_e32 v[58:59], 0
	v_mov_b64_e32 v[60:61], 0
	v_mov_b64_e32 v[62:63], 0
	v_mov_b64_e32 v[64:65], 0
	v_mov_b64_e32 v[66:67], 0
	v_mov_b64_e32 v[68:69], 0
	v_mov_b64_e32 v[70:71], 0
	v_mov_b64_e32 v[72:73], 0
	v_mov_b64_e32 v[74:75], 0
	v_mov_b64_e32 v[76:77], 0
	v_mov_b64_e32 v[78:79], 0
	v_mov_b64_e32 v[80:81], 0
	v_mov_b64_e32 v[82:83], 0
	v_mov_b64_e32 v[84:85], 0
	v_mov_b64_e32 v[86:87], 0
	v_mov_b64_e32 v[88:89], 0
	v_mov_b64_e32 v[90:91], 0
	v_mov_b64_e32 v[92:93], 0
	v_mov_b64_e32 v[94:95], 0
	v_mov_b64_e32 v[96:97], 0
	v_mov_b64_e32 v[98:99], 0
	v_mov_b64_e32 v[100:101], 0
	v_mov_b64_e32 v[102:103], 0
	v_mov_b64_e32 v[104:105], 0
	v_mov_b64_e32 v[106:107], 0
	v_mov_b64_e32 v[108:109], 0
	v_mov_b64_e32 v[110:111], 0
	v_mov_b64_e32 v[112:113], 0
	v_mov_b64_e32 v[114:115], 0
	v_mov_b64_e32 v[116:117], 0
	v_mov_b64_e32 v[118:119], 0
	v_mov_b64_e32 v[120:121], 0
	v_mov_b64_e32 v[122:123], 0
	v_mov_b64_e32 v[124:125], 0
	v_mov_b64_e32 v[126:127], 0
	s_addc_u32 s68, s35, 0
	s_mov_b32 s69, -2
	s_waitcnt vmcnt(0)

; template <class Epi, class Sched, bool ALIGN_EPI = false, bool SP2 = false>
; __device__ __forceinline__ void gemm_phase(PG8_LAS unsigned char* lds, const Gemm g, const Sched& S, const Epi& E) {
;     ...
;         const bool has_next = S.next(ui + 1, nxt);
;         const char* nA = has_next ? (const char*)g.A + (size_t)nxt.pm * tstep : cA; const char* nB = has_next ? (const char*)g.Bt + (size_t)nxt.pn * tstep : cB;
;         for (int t = 0; t < nt; t += 2) {
;             const bool last = (t == nt - 2);
;             const char* a1 = cA + (size_t)(t + 1) * kstep;
;             const char* a2 = last ? nA : cA + (size_t)(t + 2) * kstep; const char* b2 = last ? nB : cB + (size_t)(t + 2) * kstep;
;             const char* a3 = a2 + kstep; const char* b3 = b2 + kstep;
;     ...
; #pragma unroll
;         for (int a = 0; a < 2; ++a)
; #pragma unroll
;             for (int b = 0; b < 2; ++b)
; #pragma unroll
;                 for (int m = 0; m < 4; ++m)
; #pragma unroll
;                     for (int n = 0; n < 2; ++n) acc[a][b][m][n] = (f32x4){0.f, 0.f, 0.f, 0.f};
.LBB0_1399:
	s_ashr_i32 s15, s14, 31
	s_lshl_b64 s[16:17], s[14:15], 19
	s_add_u32 s16, s54, s16
	s_addc_u32 s17, s55, s17
	s_and_b64 s[18:19], s[4:5], exec
	s_cselect_b32 s15, s17, s25
	s_cselect_b32 s21, s16, s24
	s_ashr_i32 s13, s12, 31
	s_lshl_b64 s[18:19], s[12:13], 19
	s_add_u32 s18, s74, s18
	s_addc_u32 s19, s75, s19
	s_and_b64 s[28:29], s[4:5], exec
	s_cselect_b32 s13, s19, s27
	s_cselect_b32 s57, s18, s26
	s_add_u32 s24, s24, 0x40080
	s_addc_u32 s25, s25, 0
	s_add_u32 s58, s26, 0x100
	v_mov_b64_e32 v[0:1], 0
	v_mov_b64_e32 v[2:3], 0
	v_mov_b64_e32 v[4:5], 0
	v_mov_b64_e32 v[6:7], 0
	v_mov_b64_e32 v[8:9], 0
	v_mov_b64_e32 v[10:11], 0
	v_mov_b64_e32 v[12:13], 0
	v_mov_b64_e32 v[14:15], 0
	v_mov_b64_e32 v[16:17], 0
	v_mov_b64_e32 v[18:19], 0
	v_mov_b64_e32 v[20:21], 0
	v_mov_b64_e32 v[22:23], 0
	v_mov_b64_e32 v[24:25], 0
	v_mov_b64_e32 v[26:27], 0
	v_mov_b64_e32 v[28:29], 0
	v_mov_b64_e32 v[30:31], 0
	v_mov_b64_e32 v[32:33], 0
	v_mov_b64_e32 v[34:35], 0
	v_mov_b64_e32 v[36:37], 0
	v_mov_b64_e32 v[38:39], 0
	v_mov_b64_e32 v[40:41], 0
	v_mov_b64_e32 v[42:43], 0
	v_mov_b64_e32 v[44:45], 0
	v_mov_b64_e32 v[46:47], 0
	v_mov_b64_e32 v[48:49], 0
	v_mov_b64_e32 v[50:51], 0
	v_mov_b64_e32 v[52:53], 0
	v_mov_b64_e32 v[54:55], 0
	v_mov_b64_e32 v[56:57], 0
	v_mov_b64_e32 v[58:59], 0
	v_mov_b64_e32 v[60:61], 0
	v_mov_b64_e32 v[62:63], 0
	v_mov_b64_e32 v[64:65], 0
	v_mov_b64_e32 v[66:67], 0
	v_mov_b64_e32 v[68:69], 0
	v_mov_b64_e32 v[70:71], 0
	v_mov_b64_e32 v[72:73], 0
	v_mov_b64_e32 v[74:75], 0
	v_mov_b64_e32 v[76:77], 0
	v_mov_b64_e32 v[78:79], 0
	v_mov_b64_e32 v[80:81], 0
	v_mov_b64_e32 v[82:83], 0
	v_mov_b64_e32 v[84:85], 0
	v_mov_b64_e32 v[86:87], 0
	v_mov_b64_e32 v[88:89], 0
	v_mov_b64_e32 v[90:91], 0
	v_mov_b64_e32 v[92:93], 0
	v_mov_b64_e32 v[94:95], 0
	v_mov_b64_e32 v[96:97], 0
	v_mov_b64_e32 v[98:99], 0
	v_mov_b64_e32 v[100:101], 0
	v_mov_b64_e32 v[102:103], 0
	v_mov_b64_e32 v[104:105], 0
	v_mov_b64_e32 v[106:107], 0
	v_mov_b64_e32 v[108:109], 0
	v_mov_b64_e32 v[110:111], 0
	v_mov_b64_e32 v[112:113], 0
	v_mov_b64_e32 v[114:115], 0
	v_mov_b64_e32 v[116:117], 0
	v_mov_b64_e32 v[118:119], 0
	v_mov_b64_e32 v[120:121], 0
	v_mov_b64_e32 v[122:123], 0
	v_mov_b64_e32 v[124:125], 0
	v_mov_b64_e32 v[126:127], 0
	s_addc_u32 s59, s27, 0
	s_mov_b32 s60, -2
	s_waitcnt lgkmcnt(0)
	s_waitcnt vmcnt(0)

; template <class Epi, class Sched, bool ALIGN_EPI = false, bool SP2 = false>
; __device__ __forceinline__ void gemm_phase(PG8_LAS unsigned char* lds, const Gemm g, const Sched& S, const Epi& E) {
;     ...
;         const bool has_next = S.next(ui + 1, nxt);
;         const char* nA = has_next ? (const char*)g.A + (size_t)nxt.pm * tstep : cA; const char* nB = has_next ? (const char*)g.Bt + (size_t)nxt.pn * tstep : cB;
;         for (int t = 0; t < nt; t += 2) {
;             const bool last = (t == nt - 2);
;             const char* a1 = cA + (size_t)(t + 1) * kstep;
;             const char* a2 = last ? nA : cA + (size_t)(t + 2) * kstep; const char* b2 = last ? nB : cB + (size_t)(t + 2) * kstep;
;             const char* a3 = a2 + kstep; const char* b3 = b2 + kstep;
;     ...
; #pragma unroll
;         for (int a = 0; a < 2; ++a)
; #pragma unroll
;             for (int b = 0; b < 2; ++b)
; #pragma unroll
;                 for (int m = 0; m < 4; ++m)
; #pragma unroll
;                     for (int n = 0; n < 2; ++n) acc[a][b][m][n] = (f32x4){0.f, 0.f, 0.f, 0.f};
.LBB0_1486:
	s_ashr_i32 s23, s22, 31
	s_lshl_b64 s[8:9], s[22:23], 19
	s_add_u32 s24, s92, s8
	s_addc_u32 s25, s93, s9
	s_and_b64 s[8:9], s[2:3], exec
	s_cselect_b32 s10, s25, s5
	s_cselect_b32 s11, s24, s4
	s_ashr_i32 s21, s20, 31
	s_lshl_b64 s[8:9], s[20:21], 19
	s_add_u32 s26, s90, s8
	s_addc_u32 s27, s91, s9
	s_and_b64 s[8:9], s[2:3], exec
	s_cselect_b32 s21, s27, s7
	s_cselect_b32 s23, s26, s6
	s_add_u32 s4, s4, 0x40080
	s_addc_u32 s5, s5, 0
	s_add_u32 s45, s6, 0x100
	v_mov_b64_e32 v[0:1], 0
	v_mov_b64_e32 v[2:3], 0
	v_mov_b64_e32 v[4:5], 0
	v_mov_b64_e32 v[6:7], 0
	v_mov_b64_e32 v[8:9], 0
	v_mov_b64_e32 v[10:11], 0
	v_mov_b64_e32 v[12:13], 0
	v_mov_b64_e32 v[14:15], 0
	v_mov_b64_e32 v[16:17], 0
	v_mov_b64_e32 v[18:19], 0
	v_mov_b64_e32 v[20:21], 0
	v_mov_b64_e32 v[22:23], 0
	v_mov_b64_e32 v[24:25], 0
	v_mov_b64_e32 v[26:27], 0
	v_mov_b64_e32 v[28:29], 0
	v_mov_b64_e32 v[30:31], 0
	v_mov_b64_e32 v[32:33], 0
	v_mov_b64_e32 v[34:35], 0
	v_mov_b64_e32 v[36:37], 0
	v_mov_b64_e32 v[38:39], 0
	v_mov_b64_e32 v[40:41], 0
	v_mov_b64_e32 v[42:43], 0
	v_mov_b64_e32 v[44:45], 0
	v_mov_b64_e32 v[46:47], 0
	v_mov_b64_e32 v[48:49], 0
	v_mov_b64_e32 v[50:51], 0
	v_mov_b64_e32 v[52:53], 0
	v_mov_b64_e32 v[54:55], 0
	v_mov_b64_e32 v[56:57], 0
	v_mov_b64_e32 v[58:59], 0
	v_mov_b64_e32 v[60:61], 0
	v_mov_b64_e32 v[62:63], 0
	v_mov_b64_e32 v[64:65], 0
	v_mov_b64_e32 v[66:67], 0
	v_mov_b64_e32 v[68:69], 0
	v_mov_b64_e32 v[70:71], 0
	v_mov_b64_e32 v[72:73], 0
	v_mov_b64_e32 v[74:75], 0
	v_mov_b64_e32 v[76:77], 0
	v_mov_b64_e32 v[78:79], 0
	v_mov_b64_e32 v[80:81], 0
	v_mov_b64_e32 v[82:83], 0
	v_mov_b64_e32 v[84:85], 0
	v_mov_b64_e32 v[86:87], 0
	v_mov_b64_e32 v[88:89], 0
	v_mov_b64_e32 v[90:91], 0
	v_mov_b64_e32 v[92:93], 0
	v_mov_b64_e32 v[94:95], 0
	v_mov_b64_e32 v[96:97], 0
	v_mov_b64_e32 v[98:99], 0
	v_mov_b64_e32 v[100:101], 0
	v_mov_b64_e32 v[102:103], 0
	v_mov_b64_e32 v[104:105], 0
	v_mov_b64_e32 v[106:107], 0
	v_mov_b64_e32 v[108:109], 0
	v_mov_b64_e32 v[110:111], 0
	v_mov_b64_e32 v[112:113], 0
	v_mov_b64_e32 v[114:115], 0
	v_mov_b64_e32 v[116:117], 0
	v_mov_b64_e32 v[118:119], 0
	v_mov_b64_e32 v[120:121], 0
	v_mov_b64_e32 v[122:123], 0
	v_mov_b64_e32 v[124:125], 0
	v_mov_b64_e32 v[126:127], 0
	s_addc_u32 s50, s7, 0
	s_mov_b32 s51, -2
	s_waitcnt vmcnt(0)

; template <class Epi, class Sched, bool ALIGN_EPI = false, bool SP2 = false>
; __device__ __forceinline__ void gemm_phase(PG8_LAS unsigned char* lds, const Gemm g, const Sched& S, const Epi& E) {
;     ...
;         const bool has_next = S.next(ui + 1, nxt);
;         const char* nA = has_next ? (const char*)g.A + (size_t)nxt.pm * tstep : cA; const char* nB = has_next ? (const char*)g.Bt + (size_t)nxt.pn * tstep : cB;
;         for (int t = 0; t < nt; t += 2) {
;             const bool last = (t == nt - 2);
;             const char* a1 = cA + (size_t)(t + 1) * kstep;
;             const char* a2 = last ? nA : cA + (size_t)(t + 2) * kstep; const char* b2 = last ? nB : cB + (size_t)(t + 2) * kstep;
;             const char* a3 = a2 + kstep; const char* b3 = b2 + kstep;
;     ...
; #pragma unroll
;         for (int a = 0; a < 2; ++a)
; #pragma unroll
;             for (int b = 0; b < 2; ++b)
; #pragma unroll
;                 for (int m = 0; m < 4; ++m)
; #pragma unroll
;                     for (int n = 0; n < 2; ++n) acc[a][b][m][n] = (f32x4){0.f, 0.f, 0.f, 0.f};
.LBB0_1571:
	s_add_u32 s20, s20, 0xb0080
	s_addc_u32 s21, s21, 0
	s_add_u32 s45, s22, 0x100
	v_mov_b64_e32 v[0:1], 0
	v_mov_b64_e32 v[2:3], 0
	v_mov_b64_e32 v[4:5], 0
	v_mov_b64_e32 v[6:7], 0
	v_mov_b64_e32 v[8:9], 0
	v_mov_b64_e32 v[10:11], 0
	v_mov_b64_e32 v[12:13], 0
	v_mov_b64_e32 v[14:15], 0
	v_mov_b64_e32 v[16:17], 0
	v_mov_b64_e32 v[18:19], 0
	v_mov_b64_e32 v[20:21], 0
	v_mov_b64_e32 v[22:23], 0
	v_mov_b64_e32 v[24:25], 0
	v_mov_b64_e32 v[26:27], 0
	v_mov_b64_e32 v[28:29], 0
	v_mov_b64_e32 v[30:31], 0
	v_mov_b64_e32 v[32:33], 0
	v_mov_b64_e32 v[34:35], 0
	v_mov_b64_e32 v[36:37], 0
	v_mov_b64_e32 v[38:39], 0
	v_mov_b64_e32 v[40:41], 0
	v_mov_b64_e32 v[42:43], 0
	v_mov_b64_e32 v[44:45], 0
	v_mov_b64_e32 v[46:47], 0
	v_mov_b64_e32 v[48:49], 0
	v_mov_b64_e32 v[50:51], 0
	v_mov_b64_e32 v[52:53], 0
	v_mov_b64_e32 v[54:55], 0
	v_mov_b64_e32 v[56:57], 0
	v_mov_b64_e32 v[58:59], 0
	v_mov_b64_e32 v[60:61], 0
	v_mov_b64_e32 v[62:63], 0
	v_mov_b64_e32 v[64:65], 0
	v_mov_b64_e32 v[66:67], 0
	v_mov_b64_e32 v[68:69], 0
	v_mov_b64_e32 v[70:71], 0
	v_mov_b64_e32 v[72:73], 0
	v_mov_b64_e32 v[74:75], 0
	v_mov_b64_e32 v[76:77], 0
	v_mov_b64_e32 v[78:79], 0
	v_mov_b64_e32 v[80:81], 0
	v_mov_b64_e32 v[82:83], 0
	v_mov_b64_e32 v[84:85], 0
	v_mov_b64_e32 v[86:87], 0
	v_mov_b64_e32 v[88:89], 0
	v_mov_b64_e32 v[90:91], 0
	v_mov_b64_e32 v[92:93], 0
	v_mov_b64_e32 v[94:95], 0
	v_mov_b64_e32 v[96:97], 0
	v_mov_b64_e32 v[98:99], 0
	v_mov_b64_e32 v[100:101], 0
	v_mov_b64_e32 v[102:103], 0
	v_mov_b64_e32 v[104:105], 0
	v_mov_b64_e32 v[106:107], 0
	v_mov_b64_e32 v[108:109], 0
	v_mov_b64_e32 v[110:111], 0
	v_mov_b64_e32 v[112:113], 0
	v_mov_b64_e32 v[114:115], 0
	v_mov_b64_e32 v[116:117], 0
	v_mov_b64_e32 v[118:119], 0
	v_mov_b64_e32 v[120:121], 0
	v_mov_b64_e32 v[122:123], 0
	v_mov_b64_e32 v[124:125], 0
	v_mov_b64_e32 v[126:127], 0
	s_addc_u32 s46, s23, 0
	s_mov_b32 s47, -2
	s_waitcnt vmcnt(0)

; template <class Epi, class Sched, bool ALIGN_EPI = false, bool SP2 = false>
; __device__ __forceinline__ void gemm_phase(PG8_LAS unsigned char* lds, const Gemm g, const Sched& S, const Epi& E) {
;     ...
;         const bool has_next = S.next(ui + 1, nxt);
;         const char* nA = has_next ? (const char*)g.A + (size_t)nxt.pm * tstep : cA; const char* nB = has_next ? (const char*)g.Bt + (size_t)nxt.pn * tstep : cB;
;         for (int t = 0; t < nt; t += 2) {
;             const bool last = (t == nt - 2);
;             const char* a1 = cA + (size_t)(t + 1) * kstep;
;             const char* a2 = last ? nA : cA + (size_t)(t + 2) * kstep; const char* b2 = last ? nB : cB + (size_t)(t + 2) * kstep;
;             const char* a3 = a2 + kstep; const char* b3 = b2 + kstep;
;     ...
; #pragma unroll
;         for (int a = 0; a < 2; ++a)
; #pragma unroll
;             for (int b = 0; b < 2; ++b)
; #pragma unroll
;                 for (int m = 0; m < 4; ++m)
; #pragma unroll
;                     for (int n = 0; n < 2; ++n) acc[a][b][m][n] = (f32x4){0.f, 0.f, 0.f, 0.f};
.LBB0_1665:
	s_ashr_i32 s27, s26, 31
	s_lshl_b64 s[8:9], s[26:27], 19
	s_add_u32 s28, s34, s8
	s_addc_u32 s29, s35, s9
	s_and_b64 s[8:9], s[2:3], exec
	s_cselect_b32 s10, s29, s5
	s_cselect_b32 s11, s28, s4
	s_ashr_i32 s25, s24, 31
	s_lshl_b64 s[8:9], s[24:25], 19
	s_add_u32 s30, s90, s8
	s_addc_u32 s31, s91, s9
	s_and_b64 s[8:9], s[2:3], exec
	s_cselect_b32 s25, s31, s7
	s_cselect_b32 s27, s30, s6
	s_add_u32 s4, s4, 0x40080
	s_addc_u32 s5, s5, 0
	s_add_u32 s53, s6, 0x100
	v_mov_b64_e32 v[0:1], 0
	v_mov_b64_e32 v[2:3], 0
	v_mov_b64_e32 v[4:5], 0
	v_mov_b64_e32 v[6:7], 0
	v_mov_b64_e32 v[8:9], 0
	v_mov_b64_e32 v[10:11], 0
	v_mov_b64_e32 v[12:13], 0
	v_mov_b64_e32 v[14:15], 0
	v_mov_b64_e32 v[16:17], 0
	v_mov_b64_e32 v[18:19], 0
	v_mov_b64_e32 v[20:21], 0
	v_mov_b64_e32 v[22:23], 0
	v_mov_b64_e32 v[24:25], 0
	v_mov_b64_e32 v[26:27], 0
	v_mov_b64_e32 v[28:29], 0
	v_mov_b64_e32 v[30:31], 0
	v_mov_b64_e32 v[32:33], 0
	v_mov_b64_e32 v[34:35], 0
	v_mov_b64_e32 v[36:37], 0
	v_mov_b64_e32 v[38:39], 0
	v_mov_b64_e32 v[40:41], 0
	v_mov_b64_e32 v[42:43], 0
	v_mov_b64_e32 v[44:45], 0
	v_mov_b64_e32 v[46:47], 0
	v_mov_b64_e32 v[48:49], 0
	v_mov_b64_e32 v[50:51], 0
	v_mov_b64_e32 v[52:53], 0
	v_mov_b64_e32 v[54:55], 0
	v_mov_b64_e32 v[56:57], 0
	v_mov_b64_e32 v[58:59], 0
	v_mov_b64_e32 v[60:61], 0
	v_mov_b64_e32 v[62:63], 0
	v_mov_b64_e32 v[64:65], 0
	v_mov_b64_e32 v[66:67], 0
	v_mov_b64_e32 v[68:69], 0
	v_mov_b64_e32 v[70:71], 0
	v_mov_b64_e32 v[72:73], 0
	v_mov_b64_e32 v[74:75], 0
	v_mov_b64_e32 v[76:77], 0
	v_mov_b64_e32 v[78:79], 0
	v_mov_b64_e32 v[80:81], 0
	v_mov_b64_e32 v[82:83], 0
	v_mov_b64_e32 v[84:85], 0
	v_mov_b64_e32 v[86:87], 0
	v_mov_b64_e32 v[88:89], 0
	v_mov_b64_e32 v[90:91], 0
	v_mov_b64_e32 v[92:93], 0
	v_mov_b64_e32 v[94:95], 0
	v_mov_b64_e32 v[96:97], 0
	v_mov_b64_e32 v[98:99], 0
	v_mov_b64_e32 v[100:101], 0
	v_mov_b64_e32 v[102:103], 0
	v_mov_b64_e32 v[104:105], 0
	v_mov_b64_e32 v[106:107], 0
	v_mov_b64_e32 v[108:109], 0
	v_mov_b64_e32 v[110:111], 0
	v_mov_b64_e32 v[112:113], 0
	v_mov_b64_e32 v[114:115], 0
	v_mov_b64_e32 v[116:117], 0
	v_mov_b64_e32 v[118:119], 0
	v_mov_b64_e32 v[120:121], 0
	v_mov_b64_e32 v[122:123], 0
	v_mov_b64_e32 v[124:125], 0
	v_mov_b64_e32 v[126:127], 0
	s_addc_u32 s54, s7, 0
	s_mov_b32 s55, -2
	s_waitcnt vmcnt(0)
